# GEMM prologues: second group of six LDS-DMA stages issued before the first wait/barrier (vmcnt(2) -> vmcnt(8)), on top of the early-invalidate barrier version
# baseline (speedup 1.0000x reference)
; #define PG8_STAGE(bufoff, gbase, voff) do { _Pragma("unroll") for (int _i = 0; _i < 2; ++_i) \
;         __builtin_amdgcn_global_load_lds((const unsigned*)((const char*)(gbase) + (voff)[_i]), (LAS unsigned*)(lds + (bufoff) + ldsw + _i * 8192), 16, 0, 0); } while (0)
; #define PG8_WAIT_V(n) asm volatile("s_waitcnt vmcnt(" #n ")" ::: "memory")
; #define PG8_BAR __builtin_amdgcn_s_barrier()
; #define PG8_STAGE(bufoff, gbase, voff) do { _Pragma("unroll") for (int _i = 0; _i < 2; ++_i) \
;         __builtin_amdgcn_global_load_lds((const unsigned*)((const char*)(gbase) + (voff)[_i]), (LAS unsigned*)(lds + (bufoff) + ldsw + _i * 8192), 16, 0, 0); } while (0)
; #define PG8_WAIT_V(n) asm volatile("s_waitcnt vmcnt(" #n ")" ::: "memory")
; #define PG8_BAR __builtin_amdgcn_s_barrier()
; template <class Epi, class Sched>
; __device__ __forceinline__ void gemm_phase(LAS unsigned char* lds, const Gemm g, const Sched& S, const Epi& E) {
;     ...
;     PG8_STAGE(PG8_SB(0, 0), cB, voffB); PG8_STAGE(PG8_SB(0, 1), cB + hsB, voffB); PG8_STAGE(PG8_SA(0, 0), cA, voffA); PG8_STAGE(PG8_SA(0, 1), cA + hsA, voffA);
;     if (wr == 1) PG8_BAR;
;     PG8_WAIT_V(2); PG8_BAR;
;     PG8_STAGE(PG8_SB(1, 0), cB + kstep, voffB); PG8_STAGE(PG8_SA(1, 0), cA + kstep, voffA); PG8_STAGE(PG8_SB(1, 1), cB + hsB + kstep, voffB);
;     PG8_WAIT_V(6); PG8_BAR;
.LBB0_295:
	s_lshr_b32 s9, s9, 26
	s_lshl_b32 s18, s18, 5
	s_add_i32 s9, s8, s9
	s_and_b32 s28, s18, 0x60
	s_ashr_i32 s49, s9, 6
	s_lshl_b32 s9, s19, 6
	s_lshl_b32 s24, s19, 13
	s_lshl_b32 s25, s28, 7
	s_add_u32 s18, s6, 0xfc00000
	s_addc_u32 s19, s7, 0
	s_add_u32 s20, s6, 0x13c00000
	s_addc_u32 s21, s7, 0
	s_add_u32 s22, s6, 0x16c00000
	s_addc_u32 s23, s7, 0
	s_add_i32 m0, s46, 0x18000
	v_lshl_add_u64 v[2:3], v[2:3], 0, s[4:5]
	s_nop 0
	s_nop 0
	global_load_lds_dwordx4 v[2:3], off
	v_lshl_add_u64 v[2:3], v[4:5], 0, s[4:5]
	s_add_i32 m0, s46, 0x1a000
	s_add_i32 s50, s46, 0x8000
	global_load_lds_dwordx4 v[2:3], off
	v_lshl_add_u64 v[2:3], v[10:11], 0, s[4:5]
	s_mov_b32 m0, s50
	s_add_i32 s51, s46, 0xa000
	global_load_lds_dwordx4 v[2:3], off
	v_lshl_add_u64 v[2:3], v[12:13], 0, s[4:5]
	s_mov_b32 m0, s51
	v_lshlrev_b32_e32 v5, 2, v14
	global_load_lds_dwordx4 v[2:3], off
	s_add_i32 m0, s46, 0x1c000
	v_lshl_add_u64 v[2:3], v[6:7], 0, s[4:5]
	global_load_lds_dwordx4 v[2:3], off
	v_lshl_add_u64 v[2:3], v[8:9], 0, s[4:5]
	s_add_i32 m0, s46, 0x1e000
	v_and_b32_e32 v5, 32, v5
	global_load_lds_dwordx4 v[2:3], off
	s_waitcnt vmcnt(8)
	s_barrier
	v_lshrrev_b32_e32 v3, 1, v14
	v_and_b32_e32 v3, 24, v3
	v_and_b32_e32 v2, 15, v14
	v_lshlrev_b32_e32 v4, 1, v3
	v_lshl_or_b32 v4, v2, 6, v4
	v_bitop3_b32 v6, v4, s24, v5 bitop3:0xde
	v_bitop3_b32 v143, v4, s25, v5 bitop3:0xde
	v_mov_b32_e32 v4, 0xcf
	v_or_b32_e32 v142, s9, v2
	v_bitop3_b32 v144, s9, v4, v2 bitop3:0xc8
	v_add_u32_e32 v2, v20, v18
	s_cmp_gt_i32 s8, 63
	v_or_b32_e32 v153, s28, v3
	v_add_lshl_u32 v2, v2, v19, 1
	v_mov_b32_e32 v3, v1
	s_waitcnt vmcnt(6)
	s_cselect_b64 s[24:25], -1, 0
	s_add_i32 s52, s49, -2
	v_lshl_add_u64 v[136:137], s[0:1], 0, v[2:3]
	v_add_u32_e32 v2, v17, v15
	s_cmpk_lt_u32 s26, 0x100
	v_add_u32_e32 v145, 0x80, v142
	v_add_u32_e32 v147, 0x90, v142
	v_add_u32_e32 v149, 0xa0, v142
	v_add_u32_e32 v151, 0xb0, v142
	v_add_lshl_u32 v2, v2, v16, 1
	s_cselect_b64 s[26:27], -1, 0
	v_and_b32_e32 v146, 0xcf, v145
	v_and_b32_e32 v148, 0xdf, v147
	v_and_b32_e32 v150, 0xef, v149
	v_and_b32_e32 v152, 0xff, v151
	v_lshl_add_u64 v[138:139], s[0:1], 0, v[2:3]
	s_mov_b32 s56, 0
	v_add_u32_e32 v154, 0, v6
	v_readlane_b32 s58, v254, 3
	v_readlane_b32 s57, v254, 6
	s_barrier
	s_waitcnt vmcnt(0)
	s_branch .LBB0_298

; #define PG8_STAGE(bufoff, gbase, voff) do { _Pragma("unroll") for (int _i = 0; _i < 2; ++_i) \
;         __builtin_amdgcn_global_load_lds((const unsigned*)((const char*)(gbase) + (voff)[_i]), (LAS unsigned*)(lds + (bufoff) + ldsw + _i * 8192), 16, 0, 0); } while (0)
; #define PG8_WAIT_V(n) asm volatile("s_waitcnt vmcnt(" #n ")" ::: "memory")
; #define PG8_BAR __builtin_amdgcn_s_barrier()
; #define PG8_STAGE(bufoff, gbase, voff) do { _Pragma("unroll") for (int _i = 0; _i < 2; ++_i) \
;         __builtin_amdgcn_global_load_lds((const unsigned*)((const char*)(gbase) + (voff)[_i]), (LAS unsigned*)(lds + (bufoff) + ldsw + _i * 8192), 16, 0, 0); } while (0)
; #define PG8_WAIT_V(n) asm volatile("s_waitcnt vmcnt(" #n ")" ::: "memory")
; #define PG8_BAR __builtin_amdgcn_s_barrier()
; template <class Epi, class Sched>
; __device__ __forceinline__ void gemm_phase(LAS unsigned char* lds, const Gemm g, const Sched& S, const Epi& E) {
;     ...
;     PG8_STAGE(PG8_SB(0, 0), cB, voffB); PG8_STAGE(PG8_SB(0, 1), cB + hsB, voffB); PG8_STAGE(PG8_SA(0, 0), cA, voffA); PG8_STAGE(PG8_SA(0, 1), cA + hsA, voffA);
;     if (wr == 1) PG8_BAR;
;     PG8_WAIT_V(2); PG8_BAR;
;     PG8_STAGE(PG8_SB(1, 0), cB + kstep, voffB); PG8_STAGE(PG8_SA(1, 0), cA + kstep, voffA); PG8_STAGE(PG8_SB(1, 1), cB + hsB + kstep, voffB);
;     PG8_WAIT_V(6); PG8_BAR;
.LBB0_636:
	s_add_u32 s18, s12, 0x7c00000
	s_addc_u32 s19, s13, 0
	s_add_u32 s20, s12, 0x600000
	s_addc_u32 s21, s13, 0
	s_add_i32 m0, s49, 0x18000
	v_lshl_add_u64 v[2:3], v[2:3], 0, s[4:5]
	s_nop 0
	s_nop 0
	global_load_lds_dwordx4 v[2:3], off
	v_lshl_add_u64 v[2:3], v[4:5], 0, s[4:5]
	s_add_i32 m0, s49, 0x1a000
	s_add_i32 s53, s49, 0x8000
	global_load_lds_dwordx4 v[2:3], off
	v_lshl_add_u64 v[2:3], v[10:11], 0, s[4:5]
	s_mov_b32 m0, s53
	s_add_i32 s54, s49, 0xa000
	global_load_lds_dwordx4 v[2:3], off
	v_lshl_add_u64 v[2:3], v[12:13], 0, s[4:5]
	s_mov_b32 m0, s54
	s_lshr_b32 s7, s7, 26
	global_load_lds_dwordx4 v[2:3], off
	s_add_i32 m0, s49, 0x1c000
	v_lshl_add_u64 v[2:3], v[6:7], 0, s[4:5]
	global_load_lds_dwordx4 v[2:3], off
	v_lshl_add_u64 v[2:3], v[8:9], 0, s[4:5]
	s_add_i32 m0, s49, 0x1e000
	s_add_i32 s7, s6, s7
	global_load_lds_dwordx4 v[2:3], off
	s_waitcnt vmcnt(8)
	s_barrier
	v_bfe_u32 v3, v0, 4, 2
	v_and_b32_e32 v2, 15, v0
	v_lshlrev_b32_e32 v4, 4, v3
	v_lshlrev_b32_e32 v0, 2, v0
	s_ashr_i32 s55, s7, 6
	v_lshl_or_b32 v139, s23, 6, v2
	v_lshl_or_b32 v2, v2, 6, v4
	s_lshl_b32 s7, s23, 13
	v_and_b32_e32 v0, 32, v0
	v_bitop3_b32 v4, v2, s7, v0 bitop3:0xde
	s_lshl_b32 s7, s22, 5
	s_and_b32 s56, s7, 0x60
	v_lshlrev_b32_e32 v138, 3, v3
	s_lshl_b32 s7, s56, 7
	v_bitop3_b32 v160, v2, s7, v0 bitop3:0xde
	v_or_b32_e32 v5, s56, v138
	v_lshlrev_b32_e32 v0, 5, v3
	s_cmp_gt_i32 s6, 63
	v_lshl_add_u64 v[2:3], s[12:13], 0, v[0:1]
	s_mov_b64 s[6:7], 0x800000
	v_lshlrev_b32_e32 v0, 1, v5
	v_lshl_add_u64 v[140:141], v[2:3], 0, s[6:7]
	v_lshl_add_u64 v[2:3], s[12:13], 0, v[0:1]
	v_add_u32_e32 v0, v19, v17
	v_add_lshl_u32 v0, v0, v18, 1
	s_waitcnt vmcnt(6)
	s_cselect_b64 s[22:23], -1, 0
	s_add_i32 s57, s55, -2
	v_lshl_add_u64 v[144:145], s[0:1], 0, v[0:1]
	v_add_u32_e32 v0, v16, v14
	s_cmpk_lt_u32 s24, 0x100
	s_mov_b64 s[6:7], 0x16c00000
	v_add_lshl_u32 v0, v0, v15, 1
	s_cselect_b64 s[24:25], -1, 0
	v_lshl_add_u64 v[142:143], v[2:3], 0, s[6:7]
	v_lshl_add_u64 v[146:147], s[0:1], 0, v[0:1]
	s_mov_b32 s58, 0
	v_add_u32_e32 v161, 0, v4
	v_readlane_b32 s31, v254, 8
	v_readlane_b32 s36, v254, 22
	s_barrier
	s_branch .LBB0_639

; #define PG8_STAGE(bufoff, gbase, voff) do { _Pragma("unroll") for (int _i = 0; _i < 2; ++_i) \
;         __builtin_amdgcn_global_load_lds((const unsigned*)((const char*)(gbase) + (voff)[_i]), (LAS unsigned*)(lds + (bufoff) + ldsw + _i * 8192), 16, 0, 0); } while (0)
; #define PG8_WAIT_V(n) asm volatile("s_waitcnt vmcnt(" #n ")" ::: "memory")
; #define PG8_BAR __builtin_amdgcn_s_barrier()
; #define PG8_STAGE(bufoff, gbase, voff) do { _Pragma("unroll") for (int _i = 0; _i < 2; ++_i) \
;         __builtin_amdgcn_global_load_lds((const unsigned*)((const char*)(gbase) + (voff)[_i]), (LAS unsigned*)(lds + (bufoff) + ldsw + _i * 8192), 16, 0, 0); } while (0)
; #define PG8_WAIT_V(n) asm volatile("s_waitcnt vmcnt(" #n ")" ::: "memory")
; #define PG8_BAR __builtin_amdgcn_s_barrier()
; template <class Epi, class Sched>
; __device__ __forceinline__ void gemm_phase(LAS unsigned char* lds, const Gemm g, const Sched& S, const Epi& E) {
;     ...
;     PG8_STAGE(PG8_SB(0, 0), cB, voffB); PG8_STAGE(PG8_SB(0, 1), cB + hsB, voffB); PG8_STAGE(PG8_SA(0, 0), cA, voffA); PG8_STAGE(PG8_SA(0, 1), cA + hsA, voffA);
;     if (wr == 1) PG8_BAR;
;     PG8_WAIT_V(2); PG8_BAR;
;     PG8_STAGE(PG8_SB(1, 0), cB + kstep, voffB); PG8_STAGE(PG8_SA(1, 0), cA + kstep, voffA); PG8_STAGE(PG8_SB(1, 1), cB + hsB + kstep, voffB);
;     PG8_WAIT_V(6); PG8_BAR;
.LBB0_723:
	s_add_u32 s18, s12, 0x17c00000
	s_addc_u32 s19, s13, 0
	s_add_u32 s20, s12, 0x620000
	s_addc_u32 s21, s13, 0
	s_add_i32 m0, s46, 0x18000
	v_lshl_add_u64 v[2:3], v[2:3], 0, s[4:5]
	s_nop 0
	s_nop 0
	global_load_lds_dwordx4 v[2:3], off
	v_lshl_add_u64 v[2:3], v[4:5], 0, s[4:5]
	s_add_i32 m0, s46, 0x1a000
	s_add_i32 s50, s46, 0x8000
	global_load_lds_dwordx4 v[2:3], off
	v_lshl_add_u64 v[2:3], v[10:11], 0, s[4:5]
	s_mov_b32 m0, s50
	s_add_i32 s51, s46, 0xa000
	global_load_lds_dwordx4 v[2:3], off
	v_lshl_add_u64 v[2:3], v[12:13], 0, s[4:5]
	s_mov_b32 m0, s51
	s_lshr_b32 s7, s7, 26
	global_load_lds_dwordx4 v[2:3], off
	s_add_i32 m0, s46, 0x1c000
	v_lshl_add_u64 v[2:3], v[6:7], 0, s[4:5]
	global_load_lds_dwordx4 v[2:3], off
	v_lshl_add_u64 v[2:3], v[8:9], 0, s[4:5]
	s_add_i32 m0, s46, 0x1e000
	s_add_i32 s7, s6, s7
	global_load_lds_dwordx4 v[2:3], off
	s_waitcnt vmcnt(8)
	s_barrier
	v_lshrrev_b32_e32 v3, 1, v14
	v_and_b32_e32 v3, 24, v3
	v_and_b32_e32 v2, 15, v14
	v_lshlrev_b32_e32 v4, 1, v3
	v_lshl_or_b32 v144, s23, 6, v2
	v_lshl_or_b32 v2, v2, 6, v4
	v_lshlrev_b32_e32 v4, 2, v14
	s_ashr_i32 s52, s7, 6
	s_lshl_b32 s7, s23, 13
	v_and_b32_e32 v4, 32, v4
	v_bitop3_b32 v5, v2, s7, v4 bitop3:0xde
	s_lshl_b32 s7, s25, 5
	s_and_b32 s7, s7, 0x60
	s_sext_i32_i8 s57, s22
	s_lshl_b32 s22, s7, 7
	v_bitop3_b32 v145, v2, s22, v4 bitop3:0xde
	v_add_u32_e32 v2, v17, v15
	s_cmp_gt_i32 s6, 63
	v_or_b32_e32 v146, s7, v3
	v_add_lshl_u32 v2, v2, v16, 1
	v_mov_b32_e32 v3, v1
	s_waitcnt vmcnt(6)
	s_cselect_b64 s[22:23], -1, 0
	s_add_i32 s53, s52, -2
	v_lshl_add_u64 v[136:137], s[0:1], 0, v[2:3]
	v_add_u32_e32 v2, v20, v18
	s_cmpk_lt_u32 s24, 0x100
	v_add_lshl_u32 v2, v2, v19, 1
	s_cselect_b64 s[24:25], -1, 0
	v_lshl_add_u64 v[138:139], s[0:1], 0, v[2:3]
	s_mov_b32 s54, 0
	v_add_u32_e32 v147, 0, v5
	s_barrier
	s_branch .LBB0_726

; #define PG8_STAGE(bufoff, gbase, voff) do { _Pragma("unroll") for (int _i = 0; _i < 2; ++_i) \
;         __builtin_amdgcn_global_load_lds((const unsigned*)((const char*)(gbase) + (voff)[_i]), (LAS unsigned*)(lds + (bufoff) + ldsw + _i * 8192), 16, 0, 0); } while (0)
; #define PG8_WAIT_V(n) asm volatile("s_waitcnt vmcnt(" #n ")" ::: "memory")
; #define PG8_BAR __builtin_amdgcn_s_barrier()
; #define PG8_STAGE(bufoff, gbase, voff) do { _Pragma("unroll") for (int _i = 0; _i < 2; ++_i) \
;         __builtin_amdgcn_global_load_lds((const unsigned*)((const char*)(gbase) + (voff)[_i]), (LAS unsigned*)(lds + (bufoff) + ldsw + _i * 8192), 16, 0, 0); } while (0)
; #define PG8_WAIT_V(n) asm volatile("s_waitcnt vmcnt(" #n ")" ::: "memory")
; #define PG8_BAR __builtin_amdgcn_s_barrier()
; template <class Epi, class Sched>
; __device__ __forceinline__ void gemm_phase(LAS unsigned char* lds, const Gemm g, const Sched& S, const Epi& E) {
;     ...
;     PG8_STAGE(PG8_SB(0, 0), cB, voffB); PG8_STAGE(PG8_SB(0, 1), cB + hsB, voffB); PG8_STAGE(PG8_SA(0, 0), cA, voffA); PG8_STAGE(PG8_SA(0, 1), cA + hsA, voffA);
;     if (wr == 1) PG8_BAR;
;     PG8_WAIT_V(2); PG8_BAR;
;     PG8_STAGE(PG8_SB(1, 0), cB + kstep, voffB); PG8_STAGE(PG8_SA(1, 0), cA + kstep, voffA); PG8_STAGE(PG8_SB(1, 1), cB + hsB + kstep, voffB);
;     PG8_WAIT_V(6); PG8_BAR;
.LBB0_749:
	v_lshl_add_u64 v[10:11], s[40:41], 0, v[0:1]
	v_mov_b32_e32 v131, v1
	v_lshl_add_u64 v[12:13], s[40:41], 0, v[130:131]
	v_mov_b32_e32 v135, v1
	s_add_i32 m0, s43, 0x18000
	v_lshl_add_u64 v[10:11], v[10:11], 0, s[4:5]
	v_lshl_add_u64 v[18:19], s[38:39], 0, v[134:135]
	v_mov_b32_e32 v133, v1
	s_nop 0
	s_nop 0
	global_load_lds_dwordx4 v[10:11], off
	v_lshl_add_u64 v[10:11], v[12:13], 0, s[4:5]
	s_add_i32 m0, s43, 0x1a000
	s_add_i32 s47, s43, 0x8000
	v_lshl_add_u64 v[20:21], s[38:39], 0, v[132:133]
	global_load_lds_dwordx4 v[10:11], off
	v_lshl_add_u64 v[10:11], v[18:19], 0, s[4:5]
	s_mov_b32 m0, s47
	s_add_i32 s48, s43, 0xa000
	v_lshl_add_u64 v[14:15], s[8:9], 0, v[0:1]
	global_load_lds_dwordx4 v[10:11], off
	v_lshl_add_u64 v[10:11], v[20:21], 0, s[4:5]
	s_mov_b32 m0, s48
	v_lshl_add_u64 v[16:17], s[8:9], 0, v[130:131]
	global_load_lds_dwordx4 v[10:11], off
	s_add_i32 m0, s43, 0x1c000
	v_lshl_add_u64 v[10:11], v[14:15], 0, s[4:5]
	global_load_lds_dwordx4 v[10:11], off
	v_lshl_add_u64 v[10:11], v[16:17], 0, s[4:5]
	s_add_i32 m0, s43, 0x1e000
	s_lshr_b32 s7, s7, 26
	global_load_lds_dwordx4 v[10:11], off
	s_waitcnt vmcnt(8)
	s_barrier
	v_lshrrev_b32_e32 v10, 1, v2
	v_and_b32_e32 v10, 24, v10
	v_and_b32_e32 v9, 15, v2
	s_add_i32 s7, s6, s7
	v_lshlrev_b32_e32 v11, 1, v10
	v_lshlrev_b32_e32 v2, 2, v2
	s_ashr_i32 s49, s7, 6
	v_lshl_or_b32 v140, s23, 6, v9
	v_lshl_or_b32 v9, v9, 6, v11
	s_lshl_b32 s7, s23, 13
	v_and_b32_e32 v2, 32, v2
	v_bitop3_b32 v11, v9, s7, v2 bitop3:0xde
	s_lshl_b32 s7, s22, 5
	s_and_b32 s7, s7, 0x60
	s_lshl_b32 s8, s7, 7
	v_bitop3_b32 v141, v9, s8, v2 bitop3:0xde
	s_cmp_gt_i32 s6, 63
	v_add_u32_e32 v2, v8, v6
	s_waitcnt vmcnt(6)
	s_cselect_b64 s[22:23], -1, 0
	s_add_i32 s50, s49, -2
	v_add_lshl_u32 v6, v2, v7, 1
	v_add_u32_e32 v2, v5, v3
	s_cmpk_lt_u32 s24, 0x100
	v_mov_b32_e32 v7, v1
	v_add_lshl_u32 v2, v2, v4, 1
	v_mov_b32_e32 v3, v1
	s_cselect_b64 s[24:25], -1, 0
	v_or_b32_e32 v142, s7, v10
	v_lshl_add_u64 v[136:137], s[10:11], 0, v[6:7]
	v_lshl_add_u64 v[138:139], s[10:11], 0, v[2:3]
	s_mov_b32 s51, 0
	v_add_u32_e32 v143, 0, v11
	v_readlane_b32 s53, v254, 9
	v_readlane_b32 s54, v254, 16
	s_barrier
	s_branch .LBB0_752

; #define PG8_STAGE(bufoff, gbase, voff) do { _Pragma("unroll") for (int _i = 0; _i < 2; ++_i) \
;         __builtin_amdgcn_global_load_lds((const unsigned*)((const char*)(gbase) + (voff)[_i]), (LAS unsigned*)(lds + (bufoff) + ldsw + _i * 8192), 16, 0, 0); } while (0)
; #define PG8_WAIT_V(n) asm volatile("s_waitcnt vmcnt(" #n ")" ::: "memory")
; #define PG8_BAR __builtin_amdgcn_s_barrier()
; #define PG8_STAGE(bufoff, gbase, voff) do { _Pragma("unroll") for (int _i = 0; _i < 2; ++_i) \
;         __builtin_amdgcn_global_load_lds((const unsigned*)((const char*)(gbase) + (voff)[_i]), (LAS unsigned*)(lds + (bufoff) + ldsw + _i * 8192), 16, 0, 0); } while (0)
; #define PG8_WAIT_V(n) asm volatile("s_waitcnt vmcnt(" #n ")" ::: "memory")
; #define PG8_BAR __builtin_amdgcn_s_barrier()
; template <class Epi, class Sched>
; __device__ __forceinline__ void gemm_phase(LAS unsigned char* lds, const Gemm g, const Sched& S, const Epi& E) {
;     ...
;     PG8_STAGE(PG8_SB(0, 0), cB, voffB); PG8_STAGE(PG8_SB(0, 1), cB + hsB, voffB); PG8_STAGE(PG8_SA(0, 0), cA, voffA); PG8_STAGE(PG8_SA(0, 1), cA + hsA, voffA);
;     if (wr == 1) PG8_BAR;
;     PG8_WAIT_V(2); PG8_BAR;
;     PG8_STAGE(PG8_SB(1, 0), cB + kstep, voffB); PG8_STAGE(PG8_SA(1, 0), cA + kstep, voffA); PG8_STAGE(PG8_SB(1, 1), cB + hsB + kstep, voffB);
;     PG8_WAIT_V(6); PG8_BAR;
.LBB0_775:
	s_add_u32 s12, s12, 0x1bc00000
	v_readlane_b32 s40, v255, 48
	s_addc_u32 s13, s13, 0
	v_readlane_b32 s41, v255, 49
	s_lshl_b32 s40, s40, 9
	s_ashr_i32 s41, s40, 31
	s_lshl_b64 s[40:41], s[40:41], 2
	s_waitcnt lgkmcnt(0)
	s_add_u32 s26, s26, s40
	s_addc_u32 s27, s27, s41
	s_add_u32 s8, s8, s40
	s_addc_u32 s9, s9, s41
	s_add_u32 s10, s10, s40
	s_addc_u32 s11, s11, s41
	s_add_i32 m0, s52, 0x18000
	v_lshl_add_u64 v[10:11], v[10:11], 0, s[4:5]
	s_nop 0
	s_nop 0
	global_load_lds_dwordx4 v[10:11], off
	v_lshl_add_u64 v[6:7], v[6:7], 0, s[4:5]
	s_add_i32 m0, s52, 0x1a000
	s_add_i32 s56, s52, 0x8000
	global_load_lds_dwordx4 v[6:7], off
	v_lshl_add_u64 v[6:7], v[8:9], 0, s[4:5]
	s_mov_b32 m0, s56
	s_add_i32 s57, s52, 0xa000
	global_load_lds_dwordx4 v[6:7], off
	v_lshl_add_u64 v[6:7], v[12:13], 0, s[4:5]
	s_mov_b32 m0, s57
	v_lshl_add_u64 v[4:5], v[4:5], 0, s[4:5]
	global_load_lds_dwordx4 v[6:7], off
	s_add_i32 m0, s52, 0x1c000
	v_lshl_add_u64 v[2:3], v[2:3], 0, s[4:5]
	global_load_lds_dwordx4 v[4:5], off
	s_add_i32 m0, s52, 0x1e000
	s_lshr_b32 s7, s7, 26
	global_load_lds_dwordx4 v[2:3], off
	s_waitcnt vmcnt(8)
	s_barrier
	v_lshrrev_b32_e32 v3, 1, v14
	v_and_b32_e32 v3, 24, v3
	v_and_b32_e32 v2, 15, v14
	v_lshlrev_b32_e32 v4, 1, v3
	s_add_i32 s7, s6, s7
	v_lshl_or_b32 v166, s29, 6, v2
	v_lshl_or_b32 v2, v2, 6, v4
	v_lshlrev_b32_e32 v4, 2, v14
	s_ashr_i32 s58, s7, 6
	s_lshl_b32 s7, s29, 13
	v_and_b32_e32 v4, 32, v4
	v_bitop3_b32 v5, v2, s7, v4 bitop3:0xde
	s_lshl_b32 s7, s28, 5
	s_and_b32 s7, s7, 0x60
	s_lshl_b32 s28, s7, 7
	v_bitop3_b32 v167, v2, s28, v4 bitop3:0xde
	v_add_u32_e32 v2, v20, v18
	s_cmp_gt_i32 s6, 63
	v_or_b32_e32 v168, s7, v3
	v_add_lshl_u32 v2, v2, v19, 1
	v_mov_b32_e32 v3, v1
	s_waitcnt vmcnt(6)
	s_cselect_b64 s[28:29], -1, 0
	s_add_i32 s59, s58, -2
	v_lshl_add_u64 v[148:149], s[16:17], 0, v[2:3]
	v_add_u32_e32 v2, v17, v15
	s_cmpk_lt_u32 s31, 0x100
	v_add_lshl_u32 v2, v2, v16, 1
	v_readlane_b32 s6, v254, 38
	s_cselect_b64 s[40:41], -1, 0
	v_lshl_add_u64 v[150:151], s[16:17], 0, v[2:3]
	s_mov_b32 s60, 0
	v_add_u32_e32 v169, 0, v5
	v_readlane_b32 s31, v254, 13
	s_mov_b32 s62, s6
	s_barrier
	v_readlane_b32 s7, v254, 39
	s_branch .LBB0_778

; #define PG8_STAGE(bufoff, gbase, voff) do { _Pragma("unroll") for (int _i = 0; _i < 2; ++_i) \
;         __builtin_amdgcn_global_load_lds((const unsigned*)((const char*)(gbase) + (voff)[_i]), (LAS unsigned*)(lds + (bufoff) + ldsw + _i * 8192), 16, 0, 0); } while (0)
; #define PG8_WAIT_V(n) asm volatile("s_waitcnt vmcnt(" #n ")" ::: "memory")
; #define PG8_BAR __builtin_amdgcn_s_barrier()
; #define PG8_STAGE(bufoff, gbase, voff) do { _Pragma("unroll") for (int _i = 0; _i < 2; ++_i) \
;         __builtin_amdgcn_global_load_lds((const unsigned*)((const char*)(gbase) + (voff)[_i]), (LAS unsigned*)(lds + (bufoff) + ldsw + _i * 8192), 16, 0, 0); } while (0)
; #define PG8_WAIT_V(n) asm volatile("s_waitcnt vmcnt(" #n ")" ::: "memory")
; #define PG8_BAR __builtin_amdgcn_s_barrier()
; template <class Epi>
; __device__ __forceinline__ void gemm_merge_fused(LAS unsigned char* lds, const bf16_t* Yb, const bf16_t* XBb, const bf16_t* WBR, const bf16_t* WG, const MergeOrder& S, const Epi& E) {
;     ...
;     PG8_STAGE(PG8_SB(0, 0), cB, voffB); PG8_STAGE(PG8_SB(0, 1), cB + hsB, voffB); PG8_STAGE(PG8_SA(0, 0), cA, voffA); PG8_STAGE(PG8_SA(0, 1), cA + hsA, voffA);
;     if (wr == 1) PG8_BAR;
;     PG8_WAIT_V(2); PG8_BAR;
;     PG8_STAGE(PG8_SB(1, 0), cB + kstep, voffB); PG8_STAGE(PG8_SA(1, 0), cA + kstep, voffA); PG8_STAGE(PG8_SB(1, 1), cB + hsB + kstep, voffB);
;     PG8_WAIT_V(6); PG8_BAR; }
.LBB0_1313:
	s_add_u32 s57, s8, 0x1700000
	s_addc_u32 s58, s9, 0
	s_lshl_b32 s0, s0, 5
	s_and_b32 s20, s0, 0x60
	s_lshl_b32 s7, s1, 6
	s_lshl_b32 s18, s1, 13
	s_lshl_b32 s19, s20, 7
	s_add_u32 s59, s8, 0x3c00000
	s_addc_u32 s60, s9, 0
	s_add_u32 s0, s8, 0xfc00000
	s_addc_u32 s1, s9, 0
	s_add_u32 s16, s8, 0x13c00000
	s_addc_u32 s17, s9, 0
	s_add_i32 m0, s55, 0x18000
	v_lshl_add_u64 v[2:3], v[2:3], 0, s[4:5]
	s_nop 0
	s_nop 0
	global_load_lds_dwordx4 v[2:3], off
	v_lshl_add_u64 v[2:3], v[4:5], 0, s[4:5]
	s_add_i32 m0, s55, 0x1a000
	s_add_i32 s61, s55, 0x8000
	global_load_lds_dwordx4 v[2:3], off
	v_lshl_add_u64 v[2:3], v[10:11], 0, s[4:5]
	s_mov_b32 m0, s61
	s_add_i32 s62, s55, 0xa000
	global_load_lds_dwordx4 v[2:3], off
	v_lshl_add_u64 v[2:3], v[12:13], 0, s[4:5]
	s_mov_b32 m0, s62
	v_and_b32_e32 v0, 15, v14
	global_load_lds_dwordx4 v[2:3], off
	s_add_i32 m0, s55, 0x1c000
	v_lshl_add_u64 v[2:3], v[6:7], 0, s[4:5]
	global_load_lds_dwordx4 v[2:3], off
	v_lshl_add_u64 v[2:3], v[8:9], 0, s[4:5]
	s_add_i32 m0, s55, 0x1e000
	v_lshlrev_b32_e32 v4, 2, v14
	global_load_lds_dwordx4 v[2:3], off
	s_waitcnt vmcnt(8)
	s_barrier
	v_lshrrev_b32_e32 v2, 1, v14
	v_and_b32_e32 v2, 24, v2
	v_lshlrev_b32_e32 v3, 1, v2
	v_lshl_or_b32 v3, v0, 6, v3
	v_and_b32_e32 v4, 32, v4
	v_bitop3_b32 v5, v3, s18, v4 bitop3:0xde
	v_bitop3_b32 v238, v3, s19, v4 bitop3:0xde
	s_waitcnt vmcnt(6)
	v_mov_b32_e32 v3, 0xcf
	v_or_b32_e32 v237, s7, v0
	s_cmpk_lt_u32 s6, 0x100
	v_bitop3_b32 v239, s7, v3, v0 bitop3:0xc8
	v_or_b32_e32 v247, s20, v2
	v_and_b32_e32 v0, 1, v15
	v_lshlrev_b32_e32 v2, 1, v18
	v_readlane_b32 s6, v254, 38
	s_cselect_b64 s[18:19], -1, 0
	v_or_b32_e32 v240, 16, v237
	v_or_b32_e32 v241, 32, v237
	v_or_b32_e32 v242, 48, v237
	v_add_u32_e32 v243, 0x80, v237
	v_add_u32_e32 v244, 0x90, v237
	v_add_u32_e32 v245, 0xa0, v237
	v_add_u32_e32 v246, 0xb0, v237
	v_lshl_add_u32 v204, v0, 6, v2
	v_add3_u32 v248, v17, v16, 64
	s_mov_b32 s31, 0
	v_add_u32_e32 v249, 0, v5
	s_mov_b32 s66, 0
	v_readlane_b32 s67, v254, 13
	s_mov_b32 s68, s6
	s_mov_b32 s69, 0
	s_mov_b32 s65, 0
	s_barrier
	v_readlane_b32 s7, v254, 39
	s_branch .LBB0_1316

; #define PG8_STAGE(bufoff, gbase, voff) do { _Pragma("unroll") for (int _i = 0; _i < 2; ++_i) \
;         __builtin_amdgcn_global_load_lds((const unsigned*)((const char*)(gbase) + (voff)[_i]), (LAS unsigned*)(lds + (bufoff) + ldsw + _i * 8192), 16, 0, 0); } while (0)
; #define PG8_WAIT_V(n) asm volatile("s_waitcnt vmcnt(" #n ")" ::: "memory")
; #define PG8_BAR __builtin_amdgcn_s_barrier()
; #define PG8_STAGE(bufoff, gbase, voff) do { _Pragma("unroll") for (int _i = 0; _i < 2; ++_i) \
;         __builtin_amdgcn_global_load_lds((const unsigned*)((const char*)(gbase) + (voff)[_i]), (LAS unsigned*)(lds + (bufoff) + ldsw + _i * 8192), 16, 0, 0); } while (0)
; #define PG8_WAIT_V(n) asm volatile("s_waitcnt vmcnt(" #n ")" ::: "memory")
; #define PG8_BAR __builtin_amdgcn_s_barrier()
; template <class Epi, class Sched>
; __device__ __forceinline__ void gemm_phase(LAS unsigned char* lds, const Gemm g, const Sched& S, const Epi& E) {
;     ...
;     PG8_STAGE(PG8_SB(0, 0), cB, voffB); PG8_STAGE(PG8_SB(0, 1), cB + hsB, voffB); PG8_STAGE(PG8_SA(0, 0), cA, voffA); PG8_STAGE(PG8_SA(0, 1), cA + hsA, voffA);
;     if (wr == 1) PG8_BAR;
;     PG8_WAIT_V(2); PG8_BAR;
;     PG8_STAGE(PG8_SB(1, 0), cB + kstep, voffB); PG8_STAGE(PG8_SA(1, 0), cA + kstep, voffA); PG8_STAGE(PG8_SB(1, 1), cB + hsB + kstep, voffB);
;     PG8_WAIT_V(6); PG8_BAR;
.LBB0_1448:
	s_add_u32 s22, s24, 0x3c00000
	v_readlane_b32 s40, v255, 50
	s_addc_u32 s23, s25, 0
	v_readlane_b32 s41, v255, 51
	s_and_b64 s[40:41], s[40:41], exec
	s_mov_b32 s29, 0x200000
	s_cselect_b32 s29, 0x400000, s29
	s_add_u32 s24, s24, s29
	s_addc_u32 s25, s25, 0
	s_add_i32 m0, s51, 0x18000
	v_lshl_add_u64 v[10:11], v[10:11], 0, s[4:5]
	s_nop 0
	s_nop 0
	global_load_lds_dwordx4 v[10:11], off
	v_lshl_add_u64 v[6:7], v[6:7], 0, s[4:5]
	s_add_i32 m0, s51, 0x1a000
	s_add_i32 s55, s51, 0x8000
	global_load_lds_dwordx4 v[6:7], off
	v_lshl_add_u64 v[6:7], v[8:9], 0, s[4:5]
	s_mov_b32 m0, s55
	s_add_i32 s56, s51, 0xa000
	global_load_lds_dwordx4 v[6:7], off
	v_lshl_add_u64 v[6:7], v[12:13], 0, s[4:5]
	s_mov_b32 m0, s56
	v_lshl_add_u64 v[4:5], v[4:5], 0, s[4:5]
	global_load_lds_dwordx4 v[6:7], off
	s_add_i32 m0, s51, 0x1c000
	v_lshl_add_u64 v[2:3], v[2:3], 0, s[4:5]
	global_load_lds_dwordx4 v[4:5], off
	s_add_i32 m0, s51, 0x1e000
	s_lshr_b32 s7, s7, 26
	global_load_lds_dwordx4 v[2:3], off
	s_waitcnt vmcnt(8)
	s_barrier
	v_bfe_u32 v3, v14, 4, 2
	v_and_b32_e32 v2, 15, v14
	v_lshlrev_b32_e32 v5, 4, v3
	s_add_i32 s7, s6, s7
	v_lshl_or_b32 v144, s26, 6, v2
	v_lshl_or_b32 v2, v2, 6, v5
	v_lshlrev_b32_e32 v5, 2, v14
	s_and_b32 s58, s27, 3
	s_ashr_i32 s59, s7, 6
	s_lshl_b32 s7, s26, 13
	v_and_b32_e32 v5, 32, v5
	v_bitop3_b32 v6, v2, s7, v5 bitop3:0xde
	s_lshl_b32 s7, s58, 12
	v_bitop3_b32 v145, v2, s7, v5 bitop3:0xde
	v_add_u32_e32 v2, v20, v18
	v_lshlrev_b32_e32 v4, 3, v3
	s_cmp_gt_i32 s6, 63
	v_cmp_eq_u32_e64 s[44:45], 0, v3
	v_add_lshl_u32 v2, v2, v19, 1
	v_mov_b32_e32 v3, v1
	s_waitcnt vmcnt(6)
	s_cselect_b64 s[26:27], -1, 0
	s_add_i32 s60, s59, -2
	v_lshl_add_u64 v[136:137], s[8:9], 0, v[2:3]
	v_add_u32_e32 v2, v17, v15
	s_cmpk_lt_u32 s28, 0x100
	v_add_lshl_u32 v2, v2, v16, 1
	v_readlane_b32 s6, v254, 38
	s_mov_b32 s57, 0
	v_lshl_or_b32 v146, s58, 5, v4
	s_cselect_b64 s[28:29], -1, 0
	v_lshl_add_u64 v[138:139], s[8:9], 0, v[2:3]
	v_add_u32_e32 v147, 0, v6
	v_readlane_b32 s31, v254, 13
	s_mov_b32 s36, s6
	s_barrier
	v_readlane_b32 s7, v254, 39
	s_branch .LBB0_1451

; #define PG8_STAGE(bufoff, gbase, voff) do { _Pragma("unroll") for (int _i = 0; _i < 2; ++_i) \
;         __builtin_amdgcn_global_load_lds((const unsigned*)((const char*)(gbase) + (voff)[_i]), (LAS unsigned*)(lds + (bufoff) + ldsw + _i * 8192), 16, 0, 0); } while (0)
; #define PG8_WAIT_V(n) asm volatile("s_waitcnt vmcnt(" #n ")" ::: "memory")
; #define PG8_BAR __builtin_amdgcn_s_barrier()
; #define PG8_STAGE(bufoff, gbase, voff) do { _Pragma("unroll") for (int _i = 0; _i < 2; ++_i) \
;         __builtin_amdgcn_global_load_lds((const unsigned*)((const char*)(gbase) + (voff)[_i]), (LAS unsigned*)(lds + (bufoff) + ldsw + _i * 8192), 16, 0, 0); } while (0)
; #define PG8_WAIT_V(n) asm volatile("s_waitcnt vmcnt(" #n ")" ::: "memory")
; #define PG8_BAR __builtin_amdgcn_s_barrier()
; template <class Epi, class Sched>
; __device__ __forceinline__ void gemm_phase(LAS unsigned char* lds, const Gemm g, const Sched& S, const Epi& E) {
;     ...
;     PG8_STAGE(PG8_SB(0, 0), cB, voffB); PG8_STAGE(PG8_SB(0, 1), cB + hsB, voffB); PG8_STAGE(PG8_SA(0, 0), cA, voffA); PG8_STAGE(PG8_SA(0, 1), cA + hsA, voffA);
;     if (wr == 1) PG8_BAR;
;     PG8_WAIT_V(2); PG8_BAR;
;     PG8_STAGE(PG8_SB(1, 0), cB + kstep, voffB); PG8_STAGE(PG8_SA(1, 0), cA + kstep, voffA); PG8_STAGE(PG8_SB(1, 1), cB + hsB + kstep, voffB);
;     PG8_WAIT_V(6); PG8_BAR;
.LBB0_1553:
	s_lshr_b32 s21, s21, 26
	s_lshl_b32 s18, s18, 5
	s_add_i32 s21, s20, s21
	s_and_b32 s25, s18, 0x60
	s_ashr_i32 s49, s21, 6
	s_lshl_b32 s24, s19, 6
	s_lshl_b32 s21, s19, 13
	s_lshl_b32 s23, s25, 7
	s_add_u32 s18, s6, 0xfc00000
	s_addc_u32 s19, s7, 0
	s_add_i32 m0, s42, 0x18000
	v_lshl_add_u64 v[2:3], v[2:3], 0, s[4:5]
	s_nop 0
	s_nop 0
	global_load_lds_dwordx4 v[2:3], off
	v_lshl_add_u64 v[2:3], v[4:5], 0, s[4:5]
	s_add_i32 m0, s42, 0x1a000
	s_add_i32 s50, s42, 0x8000
	global_load_lds_dwordx4 v[2:3], off
	v_lshl_add_u64 v[2:3], v[10:11], 0, s[4:5]
	s_mov_b32 m0, s50
	s_add_i32 s51, s42, 0xa000
	global_load_lds_dwordx4 v[2:3], off
	v_lshl_add_u64 v[2:3], v[12:13], 0, s[4:5]
	s_mov_b32 m0, s51
	v_lshlrev_b32_e32 v5, 2, v14
	global_load_lds_dwordx4 v[2:3], off
	s_add_i32 m0, s42, 0x1c000
	v_lshl_add_u64 v[2:3], v[6:7], 0, s[4:5]
	global_load_lds_dwordx4 v[2:3], off
	v_lshl_add_u64 v[2:3], v[8:9], 0, s[4:5]
	s_add_i32 m0, s42, 0x1e000
	v_and_b32_e32 v5, 32, v5
	global_load_lds_dwordx4 v[2:3], off
	s_waitcnt vmcnt(8)
	s_barrier
	v_lshrrev_b32_e32 v3, 1, v14
	v_and_b32_e32 v3, 24, v3
	v_and_b32_e32 v2, 15, v14
	v_lshlrev_b32_e32 v4, 1, v3
	v_lshl_or_b32 v4, v2, 6, v4
	v_bitop3_b32 v6, v4, s21, v5 bitop3:0xde
	v_bitop3_b32 v141, v4, s23, v5 bitop3:0xde
	v_mov_b32_e32 v4, 0xcf
	v_or_b32_e32 v140, s24, v2
	v_bitop3_b32 v142, s24, v4, v2 bitop3:0xc8
	v_add_u32_e32 v2, v20, v18
	s_cmp_gt_i32 s20, 63
	v_or_b32_e32 v151, s25, v3
	v_add_lshl_u32 v2, v2, v19, 1
	v_mov_b32_e32 v3, v1
	s_waitcnt vmcnt(6)
	s_cselect_b64 s[20:21], -1, 0
	s_add_i32 s52, s49, -2
	v_lshl_add_u64 v[136:137], s[8:9], 0, v[2:3]
	v_add_u32_e32 v2, v17, v15
	s_cmpk_lt_u32 s22, 0x100
	v_add_u32_e32 v143, 0x80, v140
	v_add_u32_e32 v145, 0x90, v140
	v_add_u32_e32 v147, 0xa0, v140
	v_add_u32_e32 v149, 0xb0, v140
	v_add_lshl_u32 v2, v2, v16, 1
	s_cselect_b64 s[22:23], -1, 0
	v_and_b32_e32 v144, 0xcf, v143
	v_and_b32_e32 v146, 0xdf, v145
	v_and_b32_e32 v148, 0xef, v147
	v_and_b32_e32 v150, 0xff, v149
	v_lshl_add_u64 v[138:139], s[8:9], 0, v[2:3]
	s_mov_b32 s56, 0
	v_add_u32_e32 v152, 0, v6
	v_readlane_b32 s57, v254, 10
	v_readlane_b32 s31, v254, 20
	s_barrier
	s_branch .LBB0_1556

; #define PG8_STAGE(bufoff, gbase, voff) do { _Pragma("unroll") for (int _i = 0; _i < 2; ++_i) \
;         __builtin_amdgcn_global_load_lds((const unsigned*)((const char*)(gbase) + (voff)[_i]), (LAS unsigned*)(lds + (bufoff) + ldsw + _i * 8192), 16, 0, 0); } while (0)
; #define PG8_WAIT_V(n) asm volatile("s_waitcnt vmcnt(" #n ")" ::: "memory")
; #define PG8_BAR __builtin_amdgcn_s_barrier()
; #define PG8_STAGE(bufoff, gbase, voff) do { _Pragma("unroll") for (int _i = 0; _i < 2; ++_i) \
;         __builtin_amdgcn_global_load_lds((const unsigned*)((const char*)(gbase) + (voff)[_i]), (LAS unsigned*)(lds + (bufoff) + ldsw + _i * 8192), 16, 0, 0); } while (0)
; #define PG8_WAIT_V(n) asm volatile("s_waitcnt vmcnt(" #n ")" ::: "memory")
; #define PG8_BAR __builtin_amdgcn_s_barrier()
; template <class Epi, class Sched>
; __device__ __forceinline__ void gemm_phase(LAS unsigned char* lds, const Gemm g, const Sched& S, const Epi& E) {
;     ...
;     PG8_STAGE(PG8_SB(0, 0), cB, voffB); PG8_STAGE(PG8_SB(0, 1), cB + hsB, voffB); PG8_STAGE(PG8_SA(0, 0), cA, voffA); PG8_STAGE(PG8_SA(0, 1), cA + hsA, voffA);
;     if (wr == 1) PG8_BAR;
;     PG8_WAIT_V(2); PG8_BAR;
;     PG8_STAGE(PG8_SB(1, 0), cB + kstep, voffB); PG8_STAGE(PG8_SA(1, 0), cA + kstep, voffA); PG8_STAGE(PG8_SB(1, 1), cB + hsB + kstep, voffB);
;     PG8_WAIT_V(6); PG8_BAR;
.LBB0_1630:
	s_add_u32 s22, s8, 0x3c00000
	s_addc_u32 s23, s9, 0
	s_and_b64 s[0:1], s[0:1], exec
	s_mov_b32 s0, 0x200000
	s_cselect_b32 s0, 0x400000, s0
	s_add_u32 s24, s8, s0
	s_addc_u32 s25, s9, 0
	s_add_i32 m0, s52, 0x18000
	v_lshl_add_u64 v[10:11], v[10:11], 0, s[4:5]
	s_nop 0
	s_nop 0
	global_load_lds_dwordx4 v[10:11], off
	v_lshl_add_u64 v[6:7], v[6:7], 0, s[4:5]
	s_add_i32 m0, s52, 0x1a000
	s_add_i32 s56, s52, 0x8000
	global_load_lds_dwordx4 v[6:7], off
	v_lshl_add_u64 v[6:7], v[8:9], 0, s[4:5]
	s_mov_b32 m0, s56
	s_add_i32 s57, s52, 0xa000
	global_load_lds_dwordx4 v[6:7], off
	v_lshl_add_u64 v[6:7], v[12:13], 0, s[4:5]
	s_mov_b32 m0, s57
	v_lshl_add_u64 v[4:5], v[4:5], 0, s[4:5]
	global_load_lds_dwordx4 v[6:7], off
	s_add_i32 m0, s52, 0x1c000
	v_lshl_add_u64 v[2:3], v[2:3], 0, s[4:5]
	global_load_lds_dwordx4 v[4:5], off
	s_add_i32 m0, s52, 0x1e000
	s_lshr_b32 s0, s7, 26
	global_load_lds_dwordx4 v[2:3], off
	s_waitcnt vmcnt(8)
	s_barrier
	v_bfe_u32 v3, v14, 4, 2
	v_and_b32_e32 v2, 15, v14
	v_lshlrev_b32_e32 v5, 4, v3
	s_add_i32 s0, s6, s0
	v_lshl_or_b32 v144, s26, 6, v2
	v_lshl_or_b32 v2, v2, 6, v5
	v_lshlrev_b32_e32 v5, 2, v14
	s_and_b32 s59, s27, 3
	s_ashr_i32 s60, s0, 6
	s_lshl_b32 s0, s26, 13
	v_and_b32_e32 v5, 32, v5
	v_bitop3_b32 v6, v2, s0, v5 bitop3:0xde
	s_lshl_b32 s0, s59, 12
	v_bitop3_b32 v145, v2, s0, v5 bitop3:0xde
	v_add_u32_e32 v2, v20, v18
	v_lshlrev_b32_e32 v4, 3, v3
	s_cmp_gt_i32 s6, 63
	v_cmp_eq_u32_e64 s[44:45], 0, v3
	v_add_lshl_u32 v2, v2, v19, 1
	v_mov_b32_e32 v3, v1
	s_waitcnt vmcnt(6)
	s_cselect_b64 s[26:27], -1, 0
	s_add_i32 s61, s60, -2
	v_lshl_add_u64 v[136:137], s[10:11], 0, v[2:3]
	v_add_u32_e32 v2, v17, v15
	s_cmpk_lt_u32 s28, 0x100
	v_add_lshl_u32 v2, v2, v16, 1
	s_mov_b32 s58, 0
	v_lshl_or_b32 v146, s59, 5, v4
	s_cselect_b64 s[28:29], -1, 0
	v_lshl_add_u64 v[138:139], s[10:11], 0, v[2:3]
	v_add_u32_e32 v147, 0, v6
	v_readlane_b32 s31, v254, 13
	v_readlane_b32 s36, v254, 36
	s_barrier
	s_branch .LBB0_1633

; #define PG8_STAGE(bufoff, gbase, voff) do { _Pragma("unroll") for (int _i = 0; _i < 2; ++_i) \
;         __builtin_amdgcn_global_load_lds((const unsigned*)((const char*)(gbase) + (voff)[_i]), (LAS unsigned*)(lds + (bufoff) + ldsw + _i * 8192), 16, 0, 0); } while (0)
; #define PG8_WAIT_V(n) asm volatile("s_waitcnt vmcnt(" #n ")" ::: "memory")
; #define PG8_BAR __builtin_amdgcn_s_barrier()
; #define PG8_STAGE(bufoff, gbase, voff) do { _Pragma("unroll") for (int _i = 0; _i < 2; ++_i) \
;         __builtin_amdgcn_global_load_lds((const unsigned*)((const char*)(gbase) + (voff)[_i]), (LAS unsigned*)(lds + (bufoff) + ldsw + _i * 8192), 16, 0, 0); } while (0)
; #define PG8_WAIT_V(n) asm volatile("s_waitcnt vmcnt(" #n ")" ::: "memory")
; #define PG8_BAR __builtin_amdgcn_s_barrier()
; template <class Epi, class Sched>
; __device__ __forceinline__ void gemm_phase(LAS unsigned char* lds, const Gemm g, const Sched& S, const Epi& E) {
;     ...
;     PG8_STAGE(PG8_SB(0, 0), cB, voffB); PG8_STAGE(PG8_SB(0, 1), cB + hsB, voffB); PG8_STAGE(PG8_SA(0, 0), cA, voffA); PG8_STAGE(PG8_SA(0, 1), cA + hsA, voffA);
;     if (wr == 1) PG8_BAR;
;     PG8_WAIT_V(2); PG8_BAR;
;     PG8_STAGE(PG8_SB(1, 0), cB + kstep, voffB); PG8_STAGE(PG8_SA(1, 0), cA + kstep, voffA); PG8_STAGE(PG8_SB(1, 1), cB + hsB + kstep, voffB);
;     PG8_WAIT_V(6); PG8_BAR;
.LBB0_1671:
	s_add_u32 s18, s8, 0x7c00000
	s_addc_u32 s19, s9, 0
	s_add_i32 m0, s41, 0x18000
	v_lshl_add_u64 v[2:3], v[2:3], 0, s[4:5]
	s_nop 0
	s_nop 0
	global_load_lds_dwordx4 v[2:3], off
	v_lshl_add_u64 v[2:3], v[4:5], 0, s[4:5]
	s_add_i32 m0, s41, 0x1a000
	s_add_i32 s45, s41, 0x8000
	global_load_lds_dwordx4 v[2:3], off
	v_lshl_add_u64 v[2:3], v[10:11], 0, s[4:5]
	s_mov_b32 m0, s45
	s_add_i32 s46, s41, 0xa000
	global_load_lds_dwordx4 v[2:3], off
	v_lshl_add_u64 v[2:3], v[12:13], 0, s[4:5]
	s_mov_b32 m0, s46
	s_lshr_b32 s7, s7, 26
	global_load_lds_dwordx4 v[2:3], off
	s_add_i32 m0, s41, 0x1c000
	v_lshl_add_u64 v[2:3], v[6:7], 0, s[4:5]
	global_load_lds_dwordx4 v[2:3], off
	v_lshl_add_u64 v[2:3], v[8:9], 0, s[4:5]
	s_add_i32 m0, s41, 0x1e000
	s_add_i32 s7, s6, s7
	global_load_lds_dwordx4 v[2:3], off
	s_waitcnt vmcnt(8)
	s_barrier
	v_lshrrev_b32_e32 v3, 1, v14
	v_and_b32_e32 v3, 24, v3
	v_and_b32_e32 v2, 15, v14
	v_lshlrev_b32_e32 v4, 1, v3
	v_lshl_or_b32 v140, s21, 6, v2
	v_lshl_or_b32 v2, v2, 6, v4
	v_lshlrev_b32_e32 v4, 2, v14
	s_ashr_i32 s47, s7, 6
	s_lshl_b32 s7, s21, 13
	v_and_b32_e32 v4, 32, v4
	v_bitop3_b32 v5, v2, s7, v4 bitop3:0xde
	s_lshl_b32 s7, s20, 5
	s_and_b32 s7, s7, 0x60
	s_lshl_b32 s8, s7, 7
	v_bitop3_b32 v141, v2, s8, v4 bitop3:0xde
	v_add_u32_e32 v2, v20, v18
	s_cmp_gt_i32 s6, 63
	v_or_b32_e32 v142, s7, v3
	v_add_lshl_u32 v2, v2, v19, 1
	v_mov_b32_e32 v3, v1
	s_waitcnt vmcnt(6)
	s_cselect_b64 s[20:21], -1, 0
	s_add_i32 s49, s47, -2
	v_lshl_add_u64 v[136:137], s[0:1], 0, v[2:3]
	v_add_u32_e32 v2, v17, v15
	s_cmpk_lt_u32 s22, 0x100
	v_add_lshl_u32 v2, v2, v16, 1
	v_readlane_b32 s6, v254, 38
	s_cselect_b64 s[22:23], -1, 0
	v_lshl_add_u64 v[138:139], s[0:1], 0, v[2:3]
	s_mov_b32 s50, 0
	v_add_u32_e32 v143, 0, v5
	v_readlane_b32 s53, v254, 13
	s_mov_b32 s54, s6
	s_barrier
	v_readlane_b32 s7, v254, 39
	s_branch .LBB0_1674

; #define PG8_STAGE(bufoff, gbase, voff) do { _Pragma("unroll") for (int _i = 0; _i < 2; ++_i) \
;         __builtin_amdgcn_global_load_lds((const unsigned*)((const char*)(gbase) + (voff)[_i]), (LAS unsigned*)(lds + (bufoff) + ldsw + _i * 8192), 16, 0, 0); } while (0)
; #define PG8_WAIT_V(n) asm volatile("s_waitcnt vmcnt(" #n ")" ::: "memory")
; #define PG8_BAR __builtin_amdgcn_s_barrier()
; #define PG8_STAGE(bufoff, gbase, voff) do { _Pragma("unroll") for (int _i = 0; _i < 2; ++_i) \
;         __builtin_amdgcn_global_load_lds((const unsigned*)((const char*)(gbase) + (voff)[_i]), (LAS unsigned*)(lds + (bufoff) + ldsw + _i * 8192), 16, 0, 0); } while (0)
; #define PG8_WAIT_V(n) asm volatile("s_waitcnt vmcnt(" #n ")" ::: "memory")
; #define PG8_BAR __builtin_amdgcn_s_barrier()
; template <class Epi, class Sched>
; __device__ __forceinline__ void gemm_phase(LAS unsigned char* lds, const Gemm g, const Sched& S, const Epi& E) {
;     ...
;     PG8_STAGE(PG8_SB(0, 0), cB, voffB); PG8_STAGE(PG8_SB(0, 1), cB + hsB, voffB); PG8_STAGE(PG8_SA(0, 0), cA, voffA); PG8_STAGE(PG8_SA(0, 1), cA + hsA, voffA);
;     if (wr == 1) PG8_BAR;
;     PG8_WAIT_V(2); PG8_BAR;
;     PG8_STAGE(PG8_SB(1, 0), cB + kstep, voffB); PG8_STAGE(PG8_SA(1, 0), cA + kstep, voffA); PG8_STAGE(PG8_SB(1, 1), cB + hsB + kstep, voffB);
;     PG8_WAIT_V(6); PG8_BAR;
.LBB0_1758:
	s_lshr_b32 s7, s7, 26
	s_and_b32 s54, s26, 3
	s_add_i32 s7, s6, s7
	v_readlane_b32 s26, v255, 50
	s_ashr_i32 s55, s7, 6
	s_lshl_b32 s7, s25, 6
	s_lshl_b32 s25, s25, 13
	s_lshl_b32 s31, s54, 12
	v_readlane_b32 s27, v255, 51
	s_and_b64 s[26:27], s[26:27], exec
	s_cselect_b32 s21, s23, s21
	s_cselect_b32 s20, s22, s20
	s_add_u32 s10, s10, 0x7c00000
	s_addc_u32 s11, s11, 0
	s_add_i32 m0, s50, 0x18000
	v_lshl_add_u64 v[2:3], v[2:3], 0, s[4:5]
	s_nop 0
	s_nop 0
	global_load_lds_dwordx4 v[2:3], off
	v_lshl_add_u64 v[2:3], v[4:5], 0, s[4:5]
	s_add_i32 m0, s50, 0x1a000
	s_add_i32 s56, s50, 0x8000
	global_load_lds_dwordx4 v[2:3], off
	v_lshl_add_u64 v[2:3], v[10:11], 0, s[4:5]
	s_mov_b32 m0, s56
	s_add_i32 s57, s50, 0xa000
	global_load_lds_dwordx4 v[2:3], off
	v_lshl_add_u64 v[2:3], v[12:13], 0, s[4:5]
	s_mov_b32 m0, s57
	s_mov_b32 s36, 0
	global_load_lds_dwordx4 v[2:3], off
	s_add_i32 m0, s50, 0x1c000
	v_lshl_add_u64 v[2:3], v[6:7], 0, s[4:5]
	global_load_lds_dwordx4 v[2:3], off
	v_lshl_add_u64 v[2:3], v[8:9], 0, s[4:5]
	s_add_i32 m0, s50, 0x1e000
	v_lshlrev_b32_e32 v6, 2, v14
	global_load_lds_dwordx4 v[2:3], off
	s_waitcnt vmcnt(8)
	s_barrier
	v_bfe_u32 v3, v14, 4, 2
	v_and_b32_e32 v2, 15, v14
	v_lshlrev_b32_e32 v4, 3, v3
	v_lshlrev_b32_e32 v5, 4, v3
	v_cmp_eq_u32_e64 s[42:43], 0, v3
	v_mov_b32_e32 v3, 0xcf
	v_or_b32_e32 v146, s7, v2
	v_lshl_or_b32 v5, v2, 6, v5
	v_bitop3_b32 v149, s7, v3, v2 bitop3:0xc8
	v_add_u32_e32 v2, v20, v18
	s_cmp_gt_i32 s6, 63
	v_add_lshl_u32 v2, v2, v19, 1
	v_mov_b32_e32 v3, v1
	v_and_b32_e32 v6, 32, v6
	s_waitcnt vmcnt(6)
	s_cselect_b64 s[22:23], -1, 0
	s_add_i32 s58, s55, -2
	v_lshl_add_u64 v[136:137], s[0:1], 0, v[2:3]
	v_add_u32_e32 v2, v17, v15
	v_bitop3_b32 v7, v5, s25, v6 bitop3:0xde
	s_cmpk_lt_u32 s24, 0x100
	v_add_u32_e32 v150, 0x80, v146
	v_add_u32_e32 v152, 0x90, v146
	v_add_u32_e32 v154, 0xa0, v146
	v_add_u32_e32 v156, 0xb0, v146
	v_add_lshl_u32 v2, v2, v16, 1
	v_readlane_b32 s6, v254, 38
	v_bitop3_b32 v147, v5, s31, v6 bitop3:0xde
	v_lshl_or_b32 v148, s54, 5, v4
	s_cselect_b64 s[24:25], -1, 0
	v_and_b32_e32 v151, 0xcf, v150
	v_and_b32_e32 v153, 0xdf, v152
	v_and_b32_e32 v155, 0xef, v154
	v_and_b32_e32 v157, 0xff, v156
	v_lshl_add_u64 v[138:139], s[0:1], 0, v[2:3]
	v_add_u32_e32 v158, 0, v7
	v_readlane_b32 s60, v254, 13
	s_mov_b32 s31, s6
	s_barrier
	v_readlane_b32 s7, v254, 39
	s_branch .LBB0_1761
